# LN wave reductions via DPP quad_perm/row_mirror + permlane16/32 swap instead of six ds_bpermute hops (bit-identical), on top of v_ln8
# speedup vs baseline: 1.0075x; 1.0043x over previous
; __device__ __forceinline__ void phase_ln(const bool HAS_H, bf16_t* zx, float* dout, const float* g, const float* b, const float* scale, const float* shift, bf16_t* H, int lane, int wave) {
;     ...
; #pragma unroll
;         for (int j = 0; j < 4; ++j) { const u32x4 w = wc_[j];
;             v[2 * j] = (f32x4){bf2f((unsigned short)(w.x & 0xffff)), bf2f((unsigned short)(w.x >> 16)), bf2f((unsigned short)(w.y & 0xffff)), bf2f((unsigned short)(w.y >> 16))};
;             v[2 * j + 1] = (f32x4){bf2f((unsigned short)(w.z & 0xffff)), bf2f((unsigned short)(w.z >> 16)), bf2f((unsigned short)(w.w & 0xffff)), bf2f((unsigned short)(w.w >> 16))}; }
; #pragma unroll
;         for (int j = 0; j < 8; ++j) s += (v[j][0] + v[j][1]) + (v[j][2] + v[j][3]);
;         const float mean = wave_sum(s) * (1.0f / DM); float s2 = 0.f;
; #pragma unroll
;         for (int j = 0; j < 8; ++j) { v[j] = v[j] - mean; s2 += (v[j][0] * v[j][0] + v[j][1] * v[j][1]) + (v[j][2] * v[j][2] + v[j][3] * v[j][3]); }
.LBB0_227:
	v_and_b32_e32 v203, 0xffff0000, v128
	v_lshlrev_b32_e32 v205, 16, v128
	v_and_b32_e32 v199, 0xffff0000, v129
	v_lshlrev_b32_e32 v201, 16, v129
	v_and_b32_e32 v202, 0xffff0000, v130
	v_lshlrev_b32_e32 v204, 16, v130
	v_and_b32_e32 v198, 0xffff0000, v131
	v_lshlrev_b32_e32 v200, 16, v131
	v_and_b32_e32 v194, 0xffff0000, v124
	v_lshlrev_b32_e32 v196, 16, v124
	v_and_b32_e32 v191, 0xffff0000, v126
	v_lshlrev_b32_e32 v190, 16, v126
	v_and_b32_e32 v131, 0xffff0000, v116
	v_lshlrev_b32_e32 v130, 16, v116
	v_and_b32_e32 v175, 0xffff0000, v117
	v_lshlrev_b32_e32 v174, 16, v117
	v_and_b32_e32 v176, 0xffff0000, v118
	v_lshlrev_b32_e32 v124, 16, v118
	v_and_b32_e32 v128, 0xffff0000, v119
	v_lshlrev_b32_e32 v126, 16, v119
	v_pk_add_f32 v[116:117], v[204:205], v[202:203]
	v_pk_add_f32 v[118:119], v[200:201], v[198:199]
	v_and_b32_e32 v195, 0xffff0000, v125
	v_pk_add_f32 v[116:117], v[116:117], v[118:119]
	v_lshlrev_b32_e32 v197, 16, v125
	v_add_f32_e32 v117, 0, v117
	v_add_f32_e32 v187, v116, v117
	v_pk_add_f32 v[116:117], v[196:197], v[194:195]
	v_and_b32_e32 v193, 0xffff0000, v127
	v_lshlrev_b32_e32 v192, 16, v127
	v_pk_add_f32 v[116:117], v[116:117], v[116:117] op_sel_hi:[0,1]
	v_and_b32_e32 v188, 0xffff0000, v120
	v_lshlrev_b32_e32 v182, 16, v120
	v_and_b32_e32 v186, 0xffff0000, v121
	v_lshlrev_b32_e32 v184, 16, v121
	v_add_f32_e32 v183, v190, v191
	v_add_f32_e32 v189, v192, v193
	v_mov_b32_e32 v185, v117
	v_and_b32_e32 v178, 0xffff0000, v122
	v_lshlrev_b32_e32 v180, 16, v122
	v_and_b32_e32 v179, 0xffff0000, v123
	v_lshlrev_b32_e32 v181, 16, v123
	v_pk_add_f32 v[118:119], v[182:183], v[188:189]
	v_pk_add_f32 v[116:117], v[184:185], v[186:187]
	v_add_f32_e32 v125, v130, v131
	v_pk_add_f32 v[116:117], v[118:119], v[116:117]
	v_pk_add_f32 v[118:119], v[180:181], v[178:179]
	v_pk_add_f32 v[116:117], v[116:117], v[116:117] op_sel_hi:[0,1]
	v_pk_add_f32 v[118:119], v[118:119], v[118:119] op_sel_hi:[0,1]
	v_add_f32_e32 v177, v174, v175
	v_mov_b32_e32 v127, v119
	v_mov_b32_e32 v129, v117
	v_pk_add_f32 v[120:121], v[124:125], v[176:177]
	v_pk_add_f32 v[116:117], v[126:127], v[128:129]
	s_nop 0
	v_pk_add_f32 v[116:117], v[120:121], v[116:117]
	s_nop 0
	v_add_f32_e32 v116, v116, v117
	s_nop 1
	v_add_f32_dpp v116, v116, v116 quad_perm:[1,0,3,2] row_mask:0xf bank_mask:0xf
	s_nop 1
	v_add_f32_dpp v116, v116, v116 quad_perm:[2,3,0,1] row_mask:0xf bank_mask:0xf
	s_nop 1
	v_add_f32_dpp v116, v116, v116 row_half_mirror row_mask:0xf bank_mask:0xf
	s_nop 1
	v_add_f32_dpp v116, v116, v116 row_mirror row_mask:0xf bank_mask:0xf
	v_mov_b32_e32 v117, v116
	s_nop 1
	v_permlane16_swap_b32_e32 v116, v117
	s_nop 1
	v_add_f32_e32 v116, v116, v117
	v_mov_b32_e32 v117, v116
	s_nop 1
	v_permlane32_swap_b32_e32 v116, v117
	s_nop 1
	v_add_f32_e32 v125, v116, v117
	v_fmac_f32_e32 v203, 0xba000000, v125
	v_fmac_f32_e32 v202, 0xba000000, v125
	v_fmac_f32_e32 v199, 0xba000000, v125
	v_fmac_f32_e32 v205, 0xba000000, v125
	v_fmac_f32_e32 v198, 0xba000000, v125
	v_fmac_f32_e32 v204, 0xba000000, v125
	v_mov_b32_e32 v118, v203
	v_mov_b32_e32 v119, v202
	v_fmac_f32_e32 v201, 0xba000000, v125
	v_fmac_f32_e32 v200, 0xba000000, v125
	v_mov_b32_e32 v116, v205
	v_mov_b32_e32 v117, v204
	v_pk_mul_f32 v[118:119], v[118:119], v[118:119]
	v_mov_b32_e32 v120, v199
	v_mov_b32_e32 v121, v198
	v_pk_fma_f32 v[116:117], v[116:117], v[116:117], v[118:119]
	v_mov_b32_e32 v118, v201
	v_mov_b32_e32 v119, v200
	v_pk_mul_f32 v[120:121], v[120:121], v[120:121]
	v_fmac_f32_e32 v195, 0xba000000, v125
	v_pk_fma_f32 v[118:119], v[118:119], v[118:119], v[120:121]
	v_fmac_f32_e32 v197, 0xba000000, v125
	v_fmac_f32_e32 v194, 0xba000000, v125
	v_fmac_f32_e32 v196, 0xba000000, v125
	v_pk_add_f32 v[116:117], v[116:117], v[118:119]
	v_mov_b32_e32 v118, v197
	v_mov_b32_e32 v119, v195
	v_mov_b32_e32 v120, v196
	v_mov_b32_e32 v121, v194
	v_pk_add_f32 v[116:117], v[116:117], v[116:117] op_sel_hi:[0,1]
	v_pk_mul_f32 v[118:119], v[118:119], v[118:119]
	v_pk_mul_f32 v[120:121], v[120:121], v[120:121]
	v_fmac_f32_e32 v190, 0xba000000, v125
	v_pk_mov_b32 v[122:123], v[120:121], v[118:119] op_sel:[1,0]
	v_mov_b32_e32 v121, v119
	v_fmac_f32_e32 v192, 0xba000000, v125
	v_fmac_f32_e32 v191, 0xba000000, v125
	v_mul_f32_e32 v116, v190, v190
	v_pk_add_f32 v[118:119], v[122:123], v[120:121]
	v_fmac_f32_e32 v193, 0xba000000, v125
	v_pk_fma_f32 v[120:121], v[190:191], v[190:191], v[116:117] op_sel_hi:[1,1,0]
	v_mul_f32_e32 v116, v192, v192
	v_pk_add_f32 v[118:119], v[118:119], v[118:119] op_sel_hi:[0,1]
	v_pk_fma_f32 v[122:123], v[192:193], v[192:193], v[116:117] op_sel_hi:[1,1,0]
; #define GAS __attribute__((address_space(1)))
; __device__ __forceinline__ unsigned cvt_pk_bf16(float lo, float hi) { const f32x2 v = {lo, hi}; const bf16x2_t b = __builtin_convertvector(v, bf16x2_t); return __builtin_bit_cast(unsigned, b); }
; __device__ __forceinline__ void phase_ln(const bool HAS_H, bf16_t* zx, float* dout, const float* g, const float* b, const float* scale, const float* shift, bf16_t* H, int lane, int wave) {
;     ...
;         for (int j = 0; j < 8; ++j) { v[j] = v[j] - mean; s2 += (v[j][0] * v[j][0] + v[j][1] * v[j][1]) + (v[j][2] * v[j][2] + v[j][3] * v[j][3]); }
;         const float rstd = 1.0f / sqrtf(wave_sum(s2) * (1.0f / DM) + LN_EPS);
; #pragma unroll
;         for (int j = 0; j < 4; ++j) { const f32x4 x0 = v[2 * j] * rstd * gg[2 * j] + bb[2 * j], x1 = v[2 * j + 1] * rstd * gg[2 * j + 1] + bb[2 * j + 1];
;             if (HAS_H) { u32x4 w; w.x = cvt_pk_bf16(x0[0], x0[1]); w.y = cvt_pk_bf16(x0[2], x0[3]); w.z = cvt_pk_bf16(x1[0], x1[1]); w.w = cvt_pk_bf16(x1[2], x1[3]);
;                 *(GAS u32x4*)(zr + 512 * j) = w;
;                 const f32x4 h0 = x0 * sc[2 * j] + sh[2 * j], h1 = x1 * sc[2 * j + 1] + sh[2 * j + 1];
;                 u32x4 hw; hw.x = cvt_pk_bf16(h0[0], h0[1]); hw.y = cvt_pk_bf16(h0[2], h0[3]); hw.z = cvt_pk_bf16(h1[0], h1[1]); hw.w = cvt_pk_bf16(h1[2], h1[3]);
;                 *(GAS u32x4*)(H + (size_t)row * DM + 8 * lane + 512 * j) = hw; }
;             else { float* orow = dout + (size_t)row * DM + 8 * lane + 512 * j; *(GAS f32x4*)(orow) = x0; *(GAS f32x4*)(orow + 4) = x1; } } }
	v_fmac_f32_e32 v186, 0xba000000, v125
	v_fmac_f32_e32 v184, 0xba000000, v125
	v_fmac_f32_e32 v188, 0xba000000, v125
	v_fmac_f32_e32 v182, 0xba000000, v125
	v_mul_f32_e32 v120, v182, v182
	v_mul_f32_e32 v122, v188, v188
	v_mul_f32_e32 v118, v184, v184
	v_mul_f32_e32 v116, v186, v186
	v_pk_add_f32 v[120:121], v[120:121], v[122:123]
	v_pk_add_f32 v[116:117], v[118:119], v[116:117]
	v_fmac_f32_e32 v179, 0xba000000, v125
	v_fmac_f32_e32 v181, 0xba000000, v125
	v_fmac_f32_e32 v178, 0xba000000, v125
	v_fmac_f32_e32 v180, 0xba000000, v125
	v_pk_add_f32 v[116:117], v[120:121], v[116:117]
	v_mov_b32_e32 v118, v181
	v_mov_b32_e32 v119, v179
	v_mov_b32_e32 v120, v180
	v_mov_b32_e32 v121, v178
	v_pk_add_f32 v[116:117], v[116:117], v[116:117] op_sel_hi:[0,1]
	v_pk_mul_f32 v[118:119], v[118:119], v[118:119]
	v_pk_mul_f32 v[120:121], v[120:121], v[120:121]
	v_fmac_f32_e32 v130, 0xba000000, v125
	v_pk_mov_b32 v[122:123], v[120:121], v[118:119] op_sel:[1,0]
	v_mov_b32_e32 v121, v119
	v_fmac_f32_e32 v174, 0xba000000, v125
	v_fmac_f32_e32 v131, 0xba000000, v125
	v_mul_f32_e32 v116, v130, v130
	v_pk_add_f32 v[118:119], v[122:123], v[120:121]
	v_fmac_f32_e32 v175, 0xba000000, v125
	v_pk_fma_f32 v[120:121], v[130:131], v[130:131], v[116:117] op_sel_hi:[1,1,0]
	v_mul_f32_e32 v116, v174, v174
	v_pk_add_f32 v[118:119], v[118:119], v[118:119] op_sel_hi:[0,1]
	v_pk_fma_f32 v[122:123], v[174:175], v[174:175], v[116:117] op_sel_hi:[1,1,0]
	v_fmac_f32_e32 v128, 0xba000000, v125
	v_fmac_f32_e32 v126, 0xba000000, v125
	v_fmac_f32_e32 v176, 0xba000000, v125
	v_fmac_f32_e32 v124, 0xba000000, v125
	v_mul_f32_e32 v120, v124, v124
	v_mul_f32_e32 v122, v176, v176
	v_mul_f32_e32 v118, v126, v126
	v_mul_f32_e32 v116, v128, v128
	v_pk_add_f32 v[120:121], v[120:121], v[122:123]
	v_pk_add_f32 v[116:117], v[118:119], v[116:117]
	v_mov_b32_e32 v122, v200
	v_pk_add_f32 v[116:117], v[120:121], v[116:117]
	v_mov_b32_e32 v120, v204
	v_add_f32_e32 v116, v116, v117
	v_mov_b32_e32 v121, v202
	v_mov_b32_e32 v202, v205
	v_mov_b32_e32 v123, v198
	s_nop 1
	v_add_f32_dpp v116, v116, v116 quad_perm:[1,0,3,2] row_mask:0xf bank_mask:0xf
	s_nop 1
	v_add_f32_dpp v116, v116, v116 quad_perm:[2,3,0,1] row_mask:0xf bank_mask:0xf
	s_nop 1
	v_add_f32_dpp v116, v116, v116 row_half_mirror row_mask:0xf bank_mask:0xf
	s_nop 1
	v_add_f32_dpp v116, v116, v116 row_mirror row_mask:0xf bank_mask:0xf
	v_mov_b32_e32 v117, v116
	s_nop 1
	v_permlane16_swap_b32_e32 v116, v117
	s_nop 1
	v_add_f32_e32 v116, v116, v117
	v_mov_b32_e32 v117, v116
	s_nop 1
	v_permlane32_swap_b32_e32 v116, v117
	s_nop 1
	v_add_f32_e32 v116, v116, v117
	v_fmamk_f32 v116, v116, 0x3a000000, v209
	v_mul_f32_e32 v117, 0x4f800000, v116
	v_cmp_gt_f32_e32 vcc, s59, v116
	s_nop 1
	v_cndmask_b32_e32 v116, v116, v117, vcc
	v_sqrt_f32_e32 v117, v116
	s_nop 0
	v_add_u32_e32 v118, -1, v117
	v_fma_f32 v119, -v118, v117, v116
	v_cmp_ge_f32_e64 s[0:1], 0, v119
	v_add_u32_e32 v119, 1, v117
	s_nop 0
	v_cndmask_b32_e64 v118, v117, v118, s[0:1]
	v_fma_f32 v117, -v119, v117, v116
	v_cmp_lt_f32_e64 s[0:1], 0, v117
	s_nop 1
	v_cndmask_b32_e64 v117, v118, v119, s[0:1]
	v_mul_f32_e32 v118, 0x37800000, v117
	v_cndmask_b32_e32 v117, v117, v118, vcc
	v_cmp_class_f32_e32 vcc, v116, v222
	s_nop 1
	v_cndmask_b32_e32 v118, v117, v116, vcc
	v_div_scale_f32 v119, s[0:1], v118, v118, 1.0
	v_rcp_f32_e32 v125, v119
	v_mov_b32_e32 v116, v201
	v_mov_b32_e32 v117, v199
	s_mov_b64 s[0:1], -1
	v_fma_f32 v127, -v119, v125, 1.0
	v_fmac_f32_e32 v125, v127, v125
	v_div_scale_f32 v127, vcc, 1.0, v118, 1.0
	v_mul_f32_e32 v129, v127, v125
	v_fma_f32 v177, -v119, v129, v127
	v_fmac_f32_e32 v129, v177, v125
	v_fma_f32 v119, -v119, v129, v127
	v_div_fmas_f32 v119, v119, v125, v129
	v_div_fixup_f32 v198, v119, v118, 1.0
	v_pk_mul_f32 v[200:201], v[202:203], v[198:199] op_sel_hi:[1,0]
	v_pk_mul_f32 v[116:117], v[116:117], v[198:199] op_sel_hi:[1,0]
	v_pk_mul_f32 v[120:121], v[120:121], v[198:199] op_sel_hi:[1,0]
	v_pk_mul_f32 v[122:123], v[122:123], v[198:199] op_sel_hi:[1,0]
	v_pk_fma_f32 v[118:119], v[6:7], v[116:117], v[10:11]
	v_pk_fma_f32 v[116:117], v[4:5], v[200:201], v[8:9]
	v_pk_fma_f32 v[122:123], v[18:19], v[122:123], v[22:23]
	v_pk_fma_f32 v[120:121], v[16:17], v[120:121], v[20:21]
	s_and_b64 vcc, exec, s[14:15]
	s_cbranch_vccz .LBB0_229
	v_add_co_u32_e32 v200, vcc, 0xfffff000, v168
	s_mov_b64 s[0:1], 0
	s_nop 0
	v_addc_co_u32_e32 v201, vcc, -1, v169, vcc
	global_store_dwordx4 v[200:201], v[116:119], off offset:-2064
	global_store_dwordx4 v[200:201], v[120:123], off offset:-2048
